# dil_merge unrolled over the thread's 4 items: all 24 loads issued first, counted waits per item
# baseline (speedup 1.0000x reference)
.LBB0_1222:
	v_mov_b32_e32 v140, v5
	v_ashrrev_i32_e32 v2, 6, v4
	v_ashrrev_i32_e32 v3, 31, v2
	v_lshlrev_b64 v[6:7], 6, v[2:3]
	v_and_b32_e32 v0, 56, v4
	v_lshl_add_u64 v[8:9], s[38:39], 0, v[6:7]
	v_lshl_add_u64 v[10:11], s[40:41], 0, v[6:7]
	v_lshl_add_u64 v[6:7], s[42:43], 0, v[6:7]
	v_lshl_add_u64 v[8:9], v[8:9], 0, v[0:1]
	v_lshl_add_u64 v[10:11], v[10:11], 0, v[0:1]
	v_lshl_add_u64 v[6:7], v[6:7], 0, v[0:1]
	global_load_dwordx2 v[60:61], v[8:9], off
	s_mov_b32 s8, 0x1000000
	global_load_dwordx2 v[62:63], v[10:11], off
	v_add_u32_e32 v4, s84, v4
	global_load_dwordx2 v[64:65], v[6:7], off
	v_lshlrev_b64 v[40:41], 10, v[2:3]
	v_and_b32_e32 v42, 0x1f8, v5
	v_lshl_add_u64 v[40:41], s[6:7], 0, v[40:41]
	v_lshlrev_b32_e32 v42, 1, v42
	v_mov_b32_e32 v43, 0
	v_lshl_add_u64 v[40:41], v[40:41], 0, v[42:43]
	global_load_dwordx4 v[66:69], v[40:41], off
	s_mov_b64 s[100:101], 0x800000
	v_lshl_add_u64 v[48:49], v[40:41], 0, s[100:101]
	global_load_dwordx4 v[70:73], v[48:49], off
	s_mov_b64 s[100:101], 0x1000000
	v_lshl_add_u64 v[48:49], v[40:41], 0, s[100:101]
	global_load_dwordx4 v[74:77], v[48:49], off
	v_mov_b32_e32 v78, v2
	v_mov_b32_e32 v79, v3
	v_add_u32_e32 v5, s12, v5
	v_ashrrev_i32_e32 v2, 6, v4
	v_ashrrev_i32_e32 v3, 31, v2
	v_lshlrev_b64 v[6:7], 6, v[2:3]
	v_and_b32_e32 v0, 56, v4
	v_lshl_add_u64 v[8:9], s[38:39], 0, v[6:7]
	v_lshl_add_u64 v[10:11], s[40:41], 0, v[6:7]
	v_lshl_add_u64 v[6:7], s[42:43], 0, v[6:7]
	v_lshl_add_u64 v[8:9], v[8:9], 0, v[0:1]
	v_lshl_add_u64 v[10:11], v[10:11], 0, v[0:1]
	v_lshl_add_u64 v[6:7], v[6:7], 0, v[0:1]
	global_load_dwordx2 v[80:81], v[8:9], off
	s_mov_b32 s8, 0x1000000
	global_load_dwordx2 v[82:83], v[10:11], off
	v_add_u32_e32 v4, s84, v4
	global_load_dwordx2 v[84:85], v[6:7], off
	v_lshlrev_b64 v[40:41], 10, v[2:3]
	v_and_b32_e32 v42, 0x1f8, v5
	v_lshl_add_u64 v[40:41], s[6:7], 0, v[40:41]
	v_lshlrev_b32_e32 v42, 1, v42
	v_mov_b32_e32 v43, 0
	v_lshl_add_u64 v[40:41], v[40:41], 0, v[42:43]
	global_load_dwordx4 v[86:89], v[40:41], off
	s_mov_b64 s[100:101], 0x800000
	v_lshl_add_u64 v[48:49], v[40:41], 0, s[100:101]
	global_load_dwordx4 v[90:93], v[48:49], off
	s_mov_b64 s[100:101], 0x1000000
	v_lshl_add_u64 v[48:49], v[40:41], 0, s[100:101]
	global_load_dwordx4 v[94:97], v[48:49], off
	v_mov_b32_e32 v98, v2
	v_mov_b32_e32 v99, v3
	v_add_u32_e32 v5, s12, v5
	v_ashrrev_i32_e32 v2, 6, v4
	v_ashrrev_i32_e32 v3, 31, v2
	v_lshlrev_b64 v[6:7], 6, v[2:3]
	v_and_b32_e32 v0, 56, v4
	v_lshl_add_u64 v[8:9], s[38:39], 0, v[6:7]
	v_lshl_add_u64 v[10:11], s[40:41], 0, v[6:7]
	v_lshl_add_u64 v[6:7], s[42:43], 0, v[6:7]
	v_lshl_add_u64 v[8:9], v[8:9], 0, v[0:1]
	v_lshl_add_u64 v[10:11], v[10:11], 0, v[0:1]
	v_lshl_add_u64 v[6:7], v[6:7], 0, v[0:1]
	global_load_dwordx2 v[100:101], v[8:9], off
	s_mov_b32 s8, 0x1000000
	global_load_dwordx2 v[102:103], v[10:11], off
	v_add_u32_e32 v4, s84, v4
	global_load_dwordx2 v[104:105], v[6:7], off
	v_lshlrev_b64 v[40:41], 10, v[2:3]
	v_and_b32_e32 v42, 0x1f8, v5
	v_lshl_add_u64 v[40:41], s[6:7], 0, v[40:41]
	v_lshlrev_b32_e32 v42, 1, v42
	v_mov_b32_e32 v43, 0
	v_lshl_add_u64 v[40:41], v[40:41], 0, v[42:43]
	global_load_dwordx4 v[106:109], v[40:41], off
	s_mov_b64 s[100:101], 0x800000
	v_lshl_add_u64 v[48:49], v[40:41], 0, s[100:101]
	global_load_dwordx4 v[110:113], v[48:49], off
	s_mov_b64 s[100:101], 0x1000000
	v_lshl_add_u64 v[48:49], v[40:41], 0, s[100:101]
	global_load_dwordx4 v[114:117], v[48:49], off
	v_mov_b32_e32 v118, v2
	v_mov_b32_e32 v119, v3
	v_add_u32_e32 v5, s12, v5
	v_ashrrev_i32_e32 v2, 6, v4
	v_ashrrev_i32_e32 v3, 31, v2
	v_lshlrev_b64 v[6:7], 6, v[2:3]
	v_and_b32_e32 v0, 56, v4
	v_lshl_add_u64 v[8:9], s[38:39], 0, v[6:7]
	v_lshl_add_u64 v[10:11], s[40:41], 0, v[6:7]
	v_lshl_add_u64 v[6:7], s[42:43], 0, v[6:7]
	v_lshl_add_u64 v[8:9], v[8:9], 0, v[0:1]
	v_lshl_add_u64 v[10:11], v[10:11], 0, v[0:1]
	v_lshl_add_u64 v[6:7], v[6:7], 0, v[0:1]
	global_load_dwordx2 v[120:121], v[8:9], off
	s_mov_b32 s8, 0x1000000
	global_load_dwordx2 v[122:123], v[10:11], off
	v_add_u32_e32 v4, s84, v4
	global_load_dwordx2 v[124:125], v[6:7], off
	v_lshlrev_b64 v[40:41], 10, v[2:3]
	v_and_b32_e32 v42, 0x1f8, v5
	v_lshl_add_u64 v[40:41], s[6:7], 0, v[40:41]
	v_lshlrev_b32_e32 v42, 1, v42
	v_mov_b32_e32 v43, 0
	v_lshl_add_u64 v[40:41], v[40:41], 0, v[42:43]
	global_load_dwordx4 v[126:129], v[40:41], off
	s_mov_b64 s[100:101], 0x800000
	v_lshl_add_u64 v[48:49], v[40:41], 0, s[100:101]
	global_load_dwordx4 v[130:133], v[48:49], off
	s_mov_b64 s[100:101], 0x1000000
	v_lshl_add_u64 v[48:49], v[40:41], 0, s[100:101]
	global_load_dwordx4 v[134:137], v[48:49], off
	v_mov_b32_e32 v138, v2
	v_mov_b32_e32 v139, v3
	v_add_u32_e32 v5, s12, v5
	v_mov_b32_e32 v5, v140
	s_waitcnt vmcnt(18)
	s_mov_b32 s8, 0x1000000
	s_nop 1
	v_mov_b32_e32 v8, v60
	v_mov_b32_e32 v9, v61
	v_mov_b32_e32 v10, v62
	v_mov_b32_e32 v11, v63
	v_mov_b32_e32 v6, v64
	v_mov_b32_e32 v7, v65
	v_mov_b32_e32 v44, v66
	v_mov_b32_e32 v45, v67
	v_mov_b32_e32 v46, v68
	v_mov_b32_e32 v47, v69
	v_mov_b32_e32 v52, v70
	v_mov_b32_e32 v53, v71
	v_mov_b32_e32 v54, v72
	v_mov_b32_e32 v55, v73
	v_mov_b32_e32 v56, v74
	v_mov_b32_e32 v57, v75
	v_mov_b32_e32 v58, v76
	v_mov_b32_e32 v59, v77
	v_mov_b32_e32 v2, v78
	v_mov_b32_e32 v3, v79
	v_max3_f32 v0, v8, v10, v6
	v_sub_f32_e32 v8, v8, v0
	v_mul_f32_e32 v8, 0x3fb8aa3b, v8
	v_exp_f32_e32 v14, v8
	v_sub_f32_e32 v8, v10, v0
	v_sub_f32_e32 v0, v6, v0
	v_mul_f32_e32 v8, 0x3fb8aa3b, v8
	v_mul_f32_e32 v0, 0x3fb8aa3b, v0
	v_exp_f32_e32 v17, v8
	v_exp_f32_e32 v16, v0
	v_mov_b32_e32 v10, v7
	v_fma_f32 v0, v9, v14, 0
	v_pk_mul_f32 v[6:7], v[10:11], v[16:17]
	s_nop 0
	v_add_f32_e32 v0, v7, v0
	v_add_f32_e32 v15, v6, v0
	v_lshlrev_b64 v[6:7], 10, v[2:3]
	v_and_b32_e32 v0, 0x1f8, v5
	v_lshl_add_u64 v[6:7], s[6:7], 0, v[6:7]
	v_lshlrev_b32_e32 v0, 1, v0
	v_lshl_add_u64 v[10:11], v[6:7], 0, v[0:1]
	v_mov_b32_e32 v6, v44
	v_mov_b32_e32 v7, v45
	v_mov_b32_e32 v8, v46
	v_mov_b32_e32 v9, v47
	v_lshlrev_b64 v[2:3], 12, v[2:3]
	v_lshl_add_u64 v[2:3], s[0:1], 0, v[2:3]
	v_lshl_add_u64 v[2:3], v[2:3], 0, v[0:1]
	v_add_u32_e32 v5, s12, v5
	v_lshlrev_b32_e32 v18, 16, v6
	v_and_b32_e32 v20, 0xffff0000, v6
	v_add_co_u32_e32 v6, vcc, s19, v10
	v_lshlrev_b32_e32 v19, 16, v7
	v_and_b32_e32 v21, 0xffff0000, v7
	v_addc_co_u32_e32 v7, vcc, 0, v11, vcc
	v_add_co_u32_e32 v10, vcc, s8, v10
	v_lshlrev_b32_e32 v22, 16, v8
	v_and_b32_e32 v24, 0xffff0000, v8
	v_lshlrev_b32_e32 v23, 16, v9
	v_and_b32_e32 v25, 0xffff0000, v9
	v_mov_b32_e32 v6, v52
	v_mov_b32_e32 v7, v53
	v_mov_b32_e32 v8, v54
	v_mov_b32_e32 v9, v55
	v_addc_co_u32_e32 v11, vcc, 0, v11, vcc
	v_mov_b32_e32 v10, v56
	v_mov_b32_e32 v11, v57
	v_mov_b32_e32 v12, v58
	v_mov_b32_e32 v13, v59
	v_pk_fma_f32 v[18:19], v[14:15], v[18:19], 0 op_sel_hi:[0,1,0]
	v_pk_fma_f32 v[20:21], v[14:15], v[20:21], 0 op_sel_hi:[0,1,0]
	v_mov_b32_e32 v30, v17
	v_rcp_f32_e32 v26, v15
	s_nop 0
	v_add_co_u32_e32 v2, vcc, 0x23c00000, v2
	s_mov_b32 s8, 0x7ffff
	s_nop 0
	v_addc_co_u32_e32 v3, vcc, 0, v3, vcc
	v_lshlrev_b32_e32 v29, 16, v7
	v_lshlrev_b32_e32 v28, 16, v6
	v_and_b32_e32 v7, 0xffff0000, v7
	v_and_b32_e32 v6, 0xffff0000, v6
	v_pk_fma_f32 v[18:19], v[30:31], v[28:29], v[18:19] op_sel_hi:[0,1,1]
	v_pk_fma_f32 v[6:7], v[30:31], v[6:7], v[20:21] op_sel_hi:[0,1,1]
	v_lshlrev_b32_e32 v21, 16, v11
	v_lshlrev_b32_e32 v20, 16, v10
	v_pk_fma_f32 v[18:19], v[16:17], v[20:21], v[18:19] op_sel_hi:[0,1,1]
	v_and_b32_e32 v11, 0xffff0000, v11
	v_and_b32_e32 v10, 0xffff0000, v10
	v_pk_fma_f32 v[6:7], v[16:17], v[10:11], v[6:7] op_sel_hi:[0,1,1]
	v_pk_mul_f32 v[10:11], v[18:19], v[26:27] op_sel_hi:[1,0]
	v_pk_fma_f32 v[18:19], v[14:15], v[22:23], 0 op_sel_hi:[0,1,0]
	v_pk_fma_f32 v[14:15], v[14:15], v[24:25], 0 op_sel_hi:[0,1,0]
	v_lshlrev_b32_e32 v21, 16, v9
	v_lshlrev_b32_e32 v20, 16, v8
	v_and_b32_e32 v9, 0xffff0000, v9
	v_and_b32_e32 v8, 0xffff0000, v8
	v_pk_fma_f32 v[8:9], v[30:31], v[8:9], v[14:15] op_sel_hi:[0,1,1]
	v_lshlrev_b32_e32 v15, 16, v13
	v_lshlrev_b32_e32 v14, 16, v12
	v_and_b32_e32 v13, 0xffff0000, v13
	v_and_b32_e32 v12, 0xffff0000, v12
	v_pk_fma_f32 v[18:19], v[30:31], v[20:21], v[18:19] op_sel_hi:[0,1,1]
	v_pk_fma_f32 v[8:9], v[16:17], v[12:13], v[8:9] op_sel_hi:[0,1,1]
	v_pk_mul_f32 v[6:7], v[6:7], v[26:27] op_sel_hi:[1,0]
	v_pk_fma_f32 v[14:15], v[16:17], v[14:15], v[18:19] op_sel_hi:[0,1,1]
	v_pk_mul_f32 v[8:9], v[8:9], v[26:27] op_sel_hi:[1,0]
	v_pk_mul_f32 v[12:13], v[14:15], v[26:27] op_sel_hi:[1,0]
	v_cvt_pk_bf16_f32 v9, v13, v9
	v_cvt_pk_bf16_f32 v8, v12, v8
	v_cvt_pk_bf16_f32 v7, v11, v7
	v_cvt_pk_bf16_f32 v6, v10, v6
	global_store_dwordx4 v[2:3], v[6:9], off offset:2048
	s_waitcnt vmcnt(13)
	s_mov_b32 s8, 0x1000000
	s_nop 1
	v_mov_b32_e32 v8, v80
	v_mov_b32_e32 v9, v81
	v_mov_b32_e32 v10, v82
	v_mov_b32_e32 v11, v83
	v_mov_b32_e32 v6, v84
	v_mov_b32_e32 v7, v85
	v_mov_b32_e32 v44, v86
	v_mov_b32_e32 v45, v87
	v_mov_b32_e32 v46, v88
	v_mov_b32_e32 v47, v89
	v_mov_b32_e32 v52, v90
	v_mov_b32_e32 v53, v91
	v_mov_b32_e32 v54, v92
	v_mov_b32_e32 v55, v93
	v_mov_b32_e32 v56, v94
	v_mov_b32_e32 v57, v95
	v_mov_b32_e32 v58, v96
	v_mov_b32_e32 v59, v97
	v_mov_b32_e32 v2, v98
	v_mov_b32_e32 v3, v99
	v_max3_f32 v0, v8, v10, v6
	v_sub_f32_e32 v8, v8, v0
	v_mul_f32_e32 v8, 0x3fb8aa3b, v8
	v_exp_f32_e32 v14, v8
	v_sub_f32_e32 v8, v10, v0
	v_sub_f32_e32 v0, v6, v0
	v_mul_f32_e32 v8, 0x3fb8aa3b, v8
	v_mul_f32_e32 v0, 0x3fb8aa3b, v0
	v_exp_f32_e32 v17, v8
	v_exp_f32_e32 v16, v0
	v_mov_b32_e32 v10, v7
	v_fma_f32 v0, v9, v14, 0
	v_pk_mul_f32 v[6:7], v[10:11], v[16:17]
	s_nop 0
	v_add_f32_e32 v0, v7, v0
	v_add_f32_e32 v15, v6, v0
	v_lshlrev_b64 v[6:7], 10, v[2:3]
	v_and_b32_e32 v0, 0x1f8, v5
	v_lshl_add_u64 v[6:7], s[6:7], 0, v[6:7]
	v_lshlrev_b32_e32 v0, 1, v0
	v_lshl_add_u64 v[10:11], v[6:7], 0, v[0:1]
	v_mov_b32_e32 v6, v44
	v_mov_b32_e32 v7, v45
	v_mov_b32_e32 v8, v46
	v_mov_b32_e32 v9, v47
	v_lshlrev_b64 v[2:3], 12, v[2:3]
	v_lshl_add_u64 v[2:3], s[0:1], 0, v[2:3]
	v_lshl_add_u64 v[2:3], v[2:3], 0, v[0:1]
	v_add_u32_e32 v5, s12, v5
	v_lshlrev_b32_e32 v18, 16, v6
	v_and_b32_e32 v20, 0xffff0000, v6
	v_add_co_u32_e32 v6, vcc, s19, v10
	v_lshlrev_b32_e32 v19, 16, v7
	v_and_b32_e32 v21, 0xffff0000, v7
	v_addc_co_u32_e32 v7, vcc, 0, v11, vcc
	v_add_co_u32_e32 v10, vcc, s8, v10
	v_lshlrev_b32_e32 v22, 16, v8
	v_and_b32_e32 v24, 0xffff0000, v8
	v_lshlrev_b32_e32 v23, 16, v9
	v_and_b32_e32 v25, 0xffff0000, v9
	v_mov_b32_e32 v6, v52
	v_mov_b32_e32 v7, v53
	v_mov_b32_e32 v8, v54
	v_mov_b32_e32 v9, v55
	v_addc_co_u32_e32 v11, vcc, 0, v11, vcc
	v_mov_b32_e32 v10, v56
	v_mov_b32_e32 v11, v57
	v_mov_b32_e32 v12, v58
	v_mov_b32_e32 v13, v59
	v_pk_fma_f32 v[18:19], v[14:15], v[18:19], 0 op_sel_hi:[0,1,0]
	v_pk_fma_f32 v[20:21], v[14:15], v[20:21], 0 op_sel_hi:[0,1,0]
	v_mov_b32_e32 v30, v17
	v_rcp_f32_e32 v26, v15
	s_nop 0
	v_add_co_u32_e32 v2, vcc, 0x23c00000, v2
	s_mov_b32 s8, 0x7ffff
	s_nop 0
	v_addc_co_u32_e32 v3, vcc, 0, v3, vcc
	v_lshlrev_b32_e32 v29, 16, v7
	v_lshlrev_b32_e32 v28, 16, v6
	v_and_b32_e32 v7, 0xffff0000, v7
	v_and_b32_e32 v6, 0xffff0000, v6
	v_pk_fma_f32 v[18:19], v[30:31], v[28:29], v[18:19] op_sel_hi:[0,1,1]
	v_pk_fma_f32 v[6:7], v[30:31], v[6:7], v[20:21] op_sel_hi:[0,1,1]
	v_lshlrev_b32_e32 v21, 16, v11
	v_lshlrev_b32_e32 v20, 16, v10
	v_pk_fma_f32 v[18:19], v[16:17], v[20:21], v[18:19] op_sel_hi:[0,1,1]
	v_and_b32_e32 v11, 0xffff0000, v11
	v_and_b32_e32 v10, 0xffff0000, v10
	v_pk_fma_f32 v[6:7], v[16:17], v[10:11], v[6:7] op_sel_hi:[0,1,1]
	v_pk_mul_f32 v[10:11], v[18:19], v[26:27] op_sel_hi:[1,0]
	v_pk_fma_f32 v[18:19], v[14:15], v[22:23], 0 op_sel_hi:[0,1,0]
	v_pk_fma_f32 v[14:15], v[14:15], v[24:25], 0 op_sel_hi:[0,1,0]
	v_lshlrev_b32_e32 v21, 16, v9
	v_lshlrev_b32_e32 v20, 16, v8
	v_and_b32_e32 v9, 0xffff0000, v9
	v_and_b32_e32 v8, 0xffff0000, v8
	v_pk_fma_f32 v[8:9], v[30:31], v[8:9], v[14:15] op_sel_hi:[0,1,1]
	v_lshlrev_b32_e32 v15, 16, v13
	v_lshlrev_b32_e32 v14, 16, v12
	v_and_b32_e32 v13, 0xffff0000, v13
	v_and_b32_e32 v12, 0xffff0000, v12
	v_pk_fma_f32 v[18:19], v[30:31], v[20:21], v[18:19] op_sel_hi:[0,1,1]
	v_pk_fma_f32 v[8:9], v[16:17], v[12:13], v[8:9] op_sel_hi:[0,1,1]
	v_pk_mul_f32 v[6:7], v[6:7], v[26:27] op_sel_hi:[1,0]
	v_pk_fma_f32 v[14:15], v[16:17], v[14:15], v[18:19] op_sel_hi:[0,1,1]
	v_pk_mul_f32 v[8:9], v[8:9], v[26:27] op_sel_hi:[1,0]
	v_pk_mul_f32 v[12:13], v[14:15], v[26:27] op_sel_hi:[1,0]
	v_cvt_pk_bf16_f32 v9, v13, v9
	v_cvt_pk_bf16_f32 v8, v12, v8
	v_cvt_pk_bf16_f32 v7, v11, v7
	v_cvt_pk_bf16_f32 v6, v10, v6
	global_store_dwordx4 v[2:3], v[6:9], off offset:2048
	s_waitcnt vmcnt(8)
	s_mov_b32 s8, 0x1000000
	s_nop 1
	v_mov_b32_e32 v8, v100
	v_mov_b32_e32 v9, v101
	v_mov_b32_e32 v10, v102
	v_mov_b32_e32 v11, v103
	v_mov_b32_e32 v6, v104
	v_mov_b32_e32 v7, v105
	v_mov_b32_e32 v44, v106
	v_mov_b32_e32 v45, v107
	v_mov_b32_e32 v46, v108
	v_mov_b32_e32 v47, v109
	v_mov_b32_e32 v52, v110
	v_mov_b32_e32 v53, v111
	v_mov_b32_e32 v54, v112
	v_mov_b32_e32 v55, v113
	v_mov_b32_e32 v56, v114
	v_mov_b32_e32 v57, v115
	v_mov_b32_e32 v58, v116
	v_mov_b32_e32 v59, v117
	v_mov_b32_e32 v2, v118
	v_mov_b32_e32 v3, v119
	v_max3_f32 v0, v8, v10, v6
	v_sub_f32_e32 v8, v8, v0
	v_mul_f32_e32 v8, 0x3fb8aa3b, v8
	v_exp_f32_e32 v14, v8
	v_sub_f32_e32 v8, v10, v0
	v_sub_f32_e32 v0, v6, v0
	v_mul_f32_e32 v8, 0x3fb8aa3b, v8
	v_mul_f32_e32 v0, 0x3fb8aa3b, v0
	v_exp_f32_e32 v17, v8
	v_exp_f32_e32 v16, v0
	v_mov_b32_e32 v10, v7
	v_fma_f32 v0, v9, v14, 0
	v_pk_mul_f32 v[6:7], v[10:11], v[16:17]
	s_nop 0
	v_add_f32_e32 v0, v7, v0
	v_add_f32_e32 v15, v6, v0
	v_lshlrev_b64 v[6:7], 10, v[2:3]
	v_and_b32_e32 v0, 0x1f8, v5
	v_lshl_add_u64 v[6:7], s[6:7], 0, v[6:7]
	v_lshlrev_b32_e32 v0, 1, v0
	v_lshl_add_u64 v[10:11], v[6:7], 0, v[0:1]
	v_mov_b32_e32 v6, v44
	v_mov_b32_e32 v7, v45
	v_mov_b32_e32 v8, v46
	v_mov_b32_e32 v9, v47
	v_lshlrev_b64 v[2:3], 12, v[2:3]
	v_lshl_add_u64 v[2:3], s[0:1], 0, v[2:3]
	v_lshl_add_u64 v[2:3], v[2:3], 0, v[0:1]
	v_add_u32_e32 v5, s12, v5
	v_lshlrev_b32_e32 v18, 16, v6
	v_and_b32_e32 v20, 0xffff0000, v6
	v_add_co_u32_e32 v6, vcc, s19, v10
	v_lshlrev_b32_e32 v19, 16, v7
	v_and_b32_e32 v21, 0xffff0000, v7
	v_addc_co_u32_e32 v7, vcc, 0, v11, vcc
	v_add_co_u32_e32 v10, vcc, s8, v10
	v_lshlrev_b32_e32 v22, 16, v8
	v_and_b32_e32 v24, 0xffff0000, v8
	v_lshlrev_b32_e32 v23, 16, v9
	v_and_b32_e32 v25, 0xffff0000, v9
	v_mov_b32_e32 v6, v52
	v_mov_b32_e32 v7, v53
	v_mov_b32_e32 v8, v54
	v_mov_b32_e32 v9, v55
	v_addc_co_u32_e32 v11, vcc, 0, v11, vcc
	v_mov_b32_e32 v10, v56
	v_mov_b32_e32 v11, v57
	v_mov_b32_e32 v12, v58
	v_mov_b32_e32 v13, v59
	v_pk_fma_f32 v[18:19], v[14:15], v[18:19], 0 op_sel_hi:[0,1,0]
	v_pk_fma_f32 v[20:21], v[14:15], v[20:21], 0 op_sel_hi:[0,1,0]
	v_mov_b32_e32 v30, v17
	v_rcp_f32_e32 v26, v15
	s_nop 0
	v_add_co_u32_e32 v2, vcc, 0x23c00000, v2
	s_mov_b32 s8, 0x7ffff
	s_nop 0
	v_addc_co_u32_e32 v3, vcc, 0, v3, vcc
	v_lshlrev_b32_e32 v29, 16, v7
	v_lshlrev_b32_e32 v28, 16, v6
	v_and_b32_e32 v7, 0xffff0000, v7
	v_and_b32_e32 v6, 0xffff0000, v6
	v_pk_fma_f32 v[18:19], v[30:31], v[28:29], v[18:19] op_sel_hi:[0,1,1]
	v_pk_fma_f32 v[6:7], v[30:31], v[6:7], v[20:21] op_sel_hi:[0,1,1]
	v_lshlrev_b32_e32 v21, 16, v11
	v_lshlrev_b32_e32 v20, 16, v10
	v_pk_fma_f32 v[18:19], v[16:17], v[20:21], v[18:19] op_sel_hi:[0,1,1]
	v_and_b32_e32 v11, 0xffff0000, v11
	v_and_b32_e32 v10, 0xffff0000, v10
	v_pk_fma_f32 v[6:7], v[16:17], v[10:11], v[6:7] op_sel_hi:[0,1,1]
	v_pk_mul_f32 v[10:11], v[18:19], v[26:27] op_sel_hi:[1,0]
	v_pk_fma_f32 v[18:19], v[14:15], v[22:23], 0 op_sel_hi:[0,1,0]
	v_pk_fma_f32 v[14:15], v[14:15], v[24:25], 0 op_sel_hi:[0,1,0]
	v_lshlrev_b32_e32 v21, 16, v9
	v_lshlrev_b32_e32 v20, 16, v8
	v_and_b32_e32 v9, 0xffff0000, v9
	v_and_b32_e32 v8, 0xffff0000, v8
	v_pk_fma_f32 v[8:9], v[30:31], v[8:9], v[14:15] op_sel_hi:[0,1,1]
	v_lshlrev_b32_e32 v15, 16, v13
	v_lshlrev_b32_e32 v14, 16, v12
	v_and_b32_e32 v13, 0xffff0000, v13
	v_and_b32_e32 v12, 0xffff0000, v12
	v_pk_fma_f32 v[18:19], v[30:31], v[20:21], v[18:19] op_sel_hi:[0,1,1]
	v_pk_fma_f32 v[8:9], v[16:17], v[12:13], v[8:9] op_sel_hi:[0,1,1]
	v_pk_mul_f32 v[6:7], v[6:7], v[26:27] op_sel_hi:[1,0]
	v_pk_fma_f32 v[14:15], v[16:17], v[14:15], v[18:19] op_sel_hi:[0,1,1]
	v_pk_mul_f32 v[8:9], v[8:9], v[26:27] op_sel_hi:[1,0]
	v_pk_mul_f32 v[12:13], v[14:15], v[26:27] op_sel_hi:[1,0]
	v_cvt_pk_bf16_f32 v9, v13, v9
	v_cvt_pk_bf16_f32 v8, v12, v8
	v_cvt_pk_bf16_f32 v7, v11, v7
	v_cvt_pk_bf16_f32 v6, v10, v6
	global_store_dwordx4 v[2:3], v[6:9], off offset:2048
	s_waitcnt vmcnt(3)
	s_mov_b32 s8, 0x1000000
	s_nop 1
	v_mov_b32_e32 v8, v120
	v_mov_b32_e32 v9, v121
	v_mov_b32_e32 v10, v122
	v_mov_b32_e32 v11, v123
	v_mov_b32_e32 v6, v124
	v_mov_b32_e32 v7, v125
	v_mov_b32_e32 v44, v126
	v_mov_b32_e32 v45, v127
	v_mov_b32_e32 v46, v128
	v_mov_b32_e32 v47, v129
	v_mov_b32_e32 v52, v130
	v_mov_b32_e32 v53, v131
	v_mov_b32_e32 v54, v132
	v_mov_b32_e32 v55, v133
	v_mov_b32_e32 v56, v134
	v_mov_b32_e32 v57, v135
	v_mov_b32_e32 v58, v136
	v_mov_b32_e32 v59, v137
	v_mov_b32_e32 v2, v138
	v_mov_b32_e32 v3, v139
	v_max3_f32 v0, v8, v10, v6
	v_sub_f32_e32 v8, v8, v0
	v_mul_f32_e32 v8, 0x3fb8aa3b, v8
	v_exp_f32_e32 v14, v8
	v_sub_f32_e32 v8, v10, v0
	v_sub_f32_e32 v0, v6, v0
	v_mul_f32_e32 v8, 0x3fb8aa3b, v8
	v_mul_f32_e32 v0, 0x3fb8aa3b, v0
	v_exp_f32_e32 v17, v8
	v_exp_f32_e32 v16, v0
	v_mov_b32_e32 v10, v7
	v_fma_f32 v0, v9, v14, 0
	v_pk_mul_f32 v[6:7], v[10:11], v[16:17]
	s_nop 0
	v_add_f32_e32 v0, v7, v0
	v_add_f32_e32 v15, v6, v0
	v_lshlrev_b64 v[6:7], 10, v[2:3]
	v_and_b32_e32 v0, 0x1f8, v5
	v_lshl_add_u64 v[6:7], s[6:7], 0, v[6:7]
	v_lshlrev_b32_e32 v0, 1, v0
	v_lshl_add_u64 v[10:11], v[6:7], 0, v[0:1]
	v_mov_b32_e32 v6, v44
	v_mov_b32_e32 v7, v45
	v_mov_b32_e32 v8, v46
	v_mov_b32_e32 v9, v47
	v_lshlrev_b64 v[2:3], 12, v[2:3]
	v_lshl_add_u64 v[2:3], s[0:1], 0, v[2:3]
	v_lshl_add_u64 v[2:3], v[2:3], 0, v[0:1]
	v_add_u32_e32 v5, s12, v5
	v_lshlrev_b32_e32 v18, 16, v6
	v_and_b32_e32 v20, 0xffff0000, v6
	v_add_co_u32_e32 v6, vcc, s19, v10
	v_lshlrev_b32_e32 v19, 16, v7
	v_and_b32_e32 v21, 0xffff0000, v7
	v_addc_co_u32_e32 v7, vcc, 0, v11, vcc
	v_add_co_u32_e32 v10, vcc, s8, v10
	v_lshlrev_b32_e32 v22, 16, v8
	v_and_b32_e32 v24, 0xffff0000, v8
	v_lshlrev_b32_e32 v23, 16, v9
	v_and_b32_e32 v25, 0xffff0000, v9
	v_mov_b32_e32 v6, v52
	v_mov_b32_e32 v7, v53
	v_mov_b32_e32 v8, v54
	v_mov_b32_e32 v9, v55
	v_addc_co_u32_e32 v11, vcc, 0, v11, vcc
	v_mov_b32_e32 v10, v56
	v_mov_b32_e32 v11, v57
	v_mov_b32_e32 v12, v58
	v_mov_b32_e32 v13, v59
	v_pk_fma_f32 v[18:19], v[14:15], v[18:19], 0 op_sel_hi:[0,1,0]
	v_pk_fma_f32 v[20:21], v[14:15], v[20:21], 0 op_sel_hi:[0,1,0]
	v_mov_b32_e32 v30, v17
	v_rcp_f32_e32 v26, v15
	s_nop 0
	v_add_co_u32_e32 v2, vcc, 0x23c00000, v2
	s_mov_b32 s8, 0x7ffff
	s_nop 0
	v_addc_co_u32_e32 v3, vcc, 0, v3, vcc
	v_lshlrev_b32_e32 v29, 16, v7
	v_lshlrev_b32_e32 v28, 16, v6
	v_and_b32_e32 v7, 0xffff0000, v7
	v_and_b32_e32 v6, 0xffff0000, v6
	v_pk_fma_f32 v[18:19], v[30:31], v[28:29], v[18:19] op_sel_hi:[0,1,1]
	v_pk_fma_f32 v[6:7], v[30:31], v[6:7], v[20:21] op_sel_hi:[0,1,1]
	v_lshlrev_b32_e32 v21, 16, v11
	v_lshlrev_b32_e32 v20, 16, v10
	v_pk_fma_f32 v[18:19], v[16:17], v[20:21], v[18:19] op_sel_hi:[0,1,1]
	v_and_b32_e32 v11, 0xffff0000, v11
	v_and_b32_e32 v10, 0xffff0000, v10
	v_pk_fma_f32 v[6:7], v[16:17], v[10:11], v[6:7] op_sel_hi:[0,1,1]
	v_pk_mul_f32 v[10:11], v[18:19], v[26:27] op_sel_hi:[1,0]
	v_pk_fma_f32 v[18:19], v[14:15], v[22:23], 0 op_sel_hi:[0,1,0]
	v_pk_fma_f32 v[14:15], v[14:15], v[24:25], 0 op_sel_hi:[0,1,0]
	v_lshlrev_b32_e32 v21, 16, v9
	v_lshlrev_b32_e32 v20, 16, v8
	v_and_b32_e32 v9, 0xffff0000, v9
	v_and_b32_e32 v8, 0xffff0000, v8
	v_pk_fma_f32 v[8:9], v[30:31], v[8:9], v[14:15] op_sel_hi:[0,1,1]
	v_lshlrev_b32_e32 v15, 16, v13
	v_lshlrev_b32_e32 v14, 16, v12
	v_and_b32_e32 v13, 0xffff0000, v13
	v_and_b32_e32 v12, 0xffff0000, v12
	v_pk_fma_f32 v[18:19], v[30:31], v[20:21], v[18:19] op_sel_hi:[0,1,1]
	v_pk_fma_f32 v[8:9], v[16:17], v[12:13], v[8:9] op_sel_hi:[0,1,1]
	v_pk_mul_f32 v[6:7], v[6:7], v[26:27] op_sel_hi:[1,0]
	v_pk_fma_f32 v[14:15], v[16:17], v[14:15], v[18:19] op_sel_hi:[0,1,1]
	v_pk_mul_f32 v[8:9], v[8:9], v[26:27] op_sel_hi:[1,0]
	v_pk_mul_f32 v[12:13], v[14:15], v[26:27] op_sel_hi:[1,0]
	v_cvt_pk_bf16_f32 v9, v13, v9
	v_cvt_pk_bf16_f32 v8, v12, v8
	v_cvt_pk_bf16_f32 v7, v11, v7
	v_cvt_pk_bf16_f32 v6, v10, v6
	global_store_dwordx4 v[2:3], v[6:9], off offset:2048
	s_or_b64 exec, exec, s[44:45]
